# v87 + skinny sample GEMM (P7, P10): the two residual loads of a thread issued before the K loop instead of after the partial-sum barrier
# baseline (speedup 1.0000x reference)
; #define MFMA16(a, b, c) __builtin_amdgcn_mfma_f32_16x16x32_bf16((a), (b), (c), 0, 0, 0)
; template <int K>
; __device__ __forceinline__ void skinny_sample_gemm(const bfu* __restrict__ A, const bfu* __restrict__ Bt, const float* __restrict__ res, float* __restrict__ pre, float* ldsf, int bid) {
;     const int tid = threadIdx.x, lane = tid & 63, wave = __builtin_amdgcn_readfirstlane(tid >> 6), l15 = lane & 15, quad = lane >> 4;
;     const int rg = bid >> 4, cg = bid & 15;
;     constexpr int KW = K / 8, NS = KW / 32;
;     const bfu* ap = A + (size_t)(MP + rg * 16 + l15) * K + wave * KW + quad * 8;
;     const bfu* bp = Bt + (size_t)(cg * 64 + l15) * K + wave * KW + quad * 8;
;     f32x4 acc[4];
; #pragma unroll
;     for (int nt = 0; nt < 4; ++nt) acc[nt] = (f32x4){0.f, 0.f, 0.f, 0.f};
; #pragma unroll
;     for (int ks = 0; ks < NS; ++ks) {
;         const bf16x8 af = ld8g(ap + ks * 32);
; #pragma unroll
;         for (int nt = 0; nt < 4; ++nt) acc[nt] = MFMA16(af, ld8g(bp + (size_t)nt * 16 * K + ks * 32), acc[nt]);
;     }
;     ...
;         const size_t row = (size_t)(rg * 16 + r);
;         pre[(MP + row) * 1024 + cg * 64 + c] = v + ALPHA * res[row * 1024 + cg * 64 + c];
.LBB0_1022:
	s_and_b64 vcc, exec, s[0:1]
	s_cbranch_vccz .LBB0_1296
	s_add_u32 s3, s66, 0x38a0c000
	s_addc_u32 s33, s67, 0
	s_add_u32 s22, s66, 0x24c00000
	s_addc_u32 s23, s67, 0
	s_add_u32 s24, s66, 0xd00000
	s_addc_u32 s25, s67, 0
	s_add_u32 s12, s66, 0x28d00000
	v_readfirstlane_b32 s4, v172
	s_addc_u32 s13, s67, 0
	s_lshr_b32 s5, s4, 6
	s_and_b32 s4, s2, -16
	s_add_i32 s6, s4, 0x4000
	v_or_b32_e32 v134, s6, v174
	s_lshl_b32 s6, s2, 6
	s_and_b32 s6, s6, 0x3c0
	v_or_b32_e32 v187, s6, v174
	v_ashrrev_i32_e32 v135, 31, v134
	v_mov_b32_e32 v129, 0
	v_lshlrev_b32_e32 v128, 12, v187
	v_lshlrev_b64 v[0:1], 12, v[134:135]
	s_mov_b32 s11, 0
	v_lshl_add_u64 v[2:3], s[24:25], 0, v[128:129]
	s_lshl_b32 s10, s5, 9
	v_lshl_add_u64 v[2:3], v[2:3], 0, s[10:11]
	v_lshl_add_u64 v[0:1], s[22:23], 0, v[0:1]
	v_mov_b32_e32 v177, v129
	v_readlane_b32 s0, v252, 1
	v_lshl_add_u64 v[0:1], v[0:1], 0, s[10:11]
	v_lshl_add_u64 v[50:51], v[2:3], 0, v[176:177]
	s_mov_b32 s7, 0x10000
	v_readlane_b32 s1, v252, 2
	v_lshl_add_u64 v[48:49], v[0:1], 0, v[176:177]
	v_add_co_u32_e32 v52, vcc, s7, v50
	s_load_dwordx2 s[98:99], s[0:1], 0x8
	s_lshl_b32 s100, s2, 8
	s_and_b32 s100, s100, 0xf00
	v_or_b32_e32 v60, s4, v194
	v_add_u32_e32 v61, 8, v60
	v_lshlrev_b32_e32 v60, 12, v60
	v_lshlrev_b32_e32 v61, 12, v61
	v_lshl_add_u32 v60, v179, 2, v60
	v_lshl_add_u32 v61, v179, 2, v61
	s_waitcnt lgkmcnt(0)
	s_add_u32 s98, s98, s100
	s_addc_u32 s99, s99, 0
	global_load_dword v62, v60, s[98:99]
	global_load_dword v63, v61, s[98:99]
	global_load_dwordx4 v[0:3], v[48:49], off
	global_load_dwordx4 v[4:7], v[50:51], off
	v_addc_co_u32_e32 v53, vcc, 0, v51, vcc
	s_mov_b32 s7, 0x20000
	v_add_co_u32_e32 v54, vcc, s7, v50
	s_mov_b32 s7, 0x30000
	s_nop 0
	v_addc_co_u32_e32 v55, vcc, 0, v51, vcc
	v_add_co_u32_e32 v56, vcc, s7, v50
	global_load_dwordx4 v[8:11], v[52:53], off
	global_load_dwordx4 v[12:15], v[54:55], off
	v_addc_co_u32_e32 v57, vcc, 0, v51, vcc
	global_load_dwordx4 v[16:19], v[56:57], off
	global_load_dwordx4 v[20:23], v[48:49], off offset:64
	global_load_dwordx4 v[24:27], v[50:51], off offset:64
	global_load_dwordx4 v[28:31], v[52:53], off offset:64
	s_waitcnt lgkmcnt(0)
	global_load_dwordx4 v[32:35], v[54:55], off offset:64
	global_load_dwordx4 v[36:39], v[56:57], off offset:64
	global_load_dwordx4 v[40:43], v[48:49], off offset:128
	global_load_dwordx4 v[44:47], v[50:51], off offset:128
	s_lshl_b32 s5, s5, 12
	v_lshlrev_b32_e32 v135, 10, v175
	v_lshlrev_b32_e32 v186, 2, v174
	s_add_i32 s5, s5, 0
	s_lshl_b32 s10, s6, 2
	v_lshlrev_b32_e32 v128, 2, v179
	s_waitcnt vmcnt(10)
	v_mfma_f32_16x16x32_bf16 v[4:7], v[0:3], v[4:7], 0
	s_waitcnt vmcnt(9)
	v_mfma_f32_16x16x32_bf16 v[8:11], v[0:3], v[8:11], 0
	s_waitcnt vmcnt(8)
	v_mfma_f32_16x16x32_bf16 v[12:15], v[0:3], v[12:15], 0
	s_waitcnt vmcnt(7)
	v_mfma_f32_16x16x32_bf16 v[0:3], v[0:3], v[16:19], 0
	global_load_dwordx4 v[16:19], v[52:53], off offset:128
	s_waitcnt vmcnt(6)
	v_mfma_f32_16x16x32_bf16 v[4:7], v[20:23], v[24:27], v[4:7]
	global_load_dwordx4 v[24:27], v[54:55], off offset:128
	s_waitcnt vmcnt(6)
	v_mfma_f32_16x16x32_bf16 v[8:11], v[20:23], v[28:31], v[8:11]
	global_load_dwordx4 v[28:31], v[56:57], off offset:128
	s_waitcnt vmcnt(6)
	v_mfma_f32_16x16x32_bf16 v[12:15], v[20:23], v[32:35], v[12:15]
	global_load_dwordx4 v[32:35], v[48:49], off offset:192
	s_waitcnt vmcnt(6)
	v_mfma_f32_16x16x32_bf16 v[0:3], v[20:23], v[36:39], v[0:3]
	global_load_dwordx4 v[20:23], v[50:51], off offset:192
	global_load_dwordx4 v[36:39], v[52:53], off offset:192
	s_waitcnt vmcnt(6)
	v_mfma_f32_16x16x32_bf16 v[4:7], v[40:43], v[44:47], v[4:7]
	s_waitcnt vmcnt(5)
	v_mfma_f32_16x16x32_bf16 v[8:11], v[40:43], v[16:19], v[8:11]
	global_load_dwordx4 v[16:19], v[54:55], off offset:192
	global_load_dwordx4 v[44:47], v[56:57], off offset:192
	s_waitcnt vmcnt(6)
	v_mfma_f32_16x16x32_bf16 v[12:15], v[40:43], v[24:27], v[12:15]
	global_load_dwordx4 v[24:27], v[48:49], off offset:256
	s_waitcnt vmcnt(6)
	v_mfma_f32_16x16x32_bf16 v[0:3], v[40:43], v[28:31], v[0:3]
	global_load_dwordx4 v[28:31], v[50:51], off offset:256
	s_waitcnt vmcnt(5)
	v_mfma_f32_16x16x32_bf16 v[4:7], v[32:35], v[20:23], v[4:7]
	global_load_dwordx4 v[20:23], v[52:53], off offset:256
	s_waitcnt vmcnt(5)
	v_mfma_f32_16x16x32_bf16 v[8:11], v[32:35], v[36:39], v[8:11]
	global_load_dwordx4 v[36:39], v[54:55], off offset:256
	global_load_dwordx4 v[40:43], v[56:57], off offset:256
	s_waitcnt vmcnt(6)
	v_mfma_f32_16x16x32_bf16 v[12:15], v[32:35], v[16:19], v[12:15]
	global_load_dwordx4 v[16:19], v[48:49], off offset:320
	s_waitcnt vmcnt(6)
	v_mfma_f32_16x16x32_bf16 v[0:3], v[32:35], v[44:47], v[0:3]
	global_load_dwordx4 v[32:35], v[50:51], off offset:320
	s_waitcnt vmcnt(5)
; #define MFMA16(a, b, c) __builtin_amdgcn_mfma_f32_16x16x32_bf16((a), (b), (c), 0, 0, 0)
; template <int K>
; __device__ __forceinline__ void skinny_sample_gemm(const bfu* __restrict__ A, const bfu* __restrict__ Bt, const float* __restrict__ res, float* __restrict__ pre, float* ldsf, int bid) {
;     ...
;     for (int ks = 0; ks < NS; ++ks) {
;         const bf16x8 af = ld8g(ap + ks * 32);
; #pragma unroll
;         for (int nt = 0; nt < 4; ++nt) acc[nt] = MFMA16(af, ld8g(bp + (size_t)nt * 16 * K + ks * 32), acc[nt]);
;     }
; #pragma unroll
;     for (int nt = 0; nt < 4; ++nt)
; #pragma unroll
;         for (int j = 0; j < 4; ++j) ldsf[wave * 1024 + (quad * 4 + j) * 64 + nt * 16 + l15] = acc[nt][j];
;     __syncthreads();
; #pragma unroll
;     for (int i = 0; i < 2; ++i) {
;         const int e = tid + 512 * i, r = e >> 6, c = e & 63;
;         float v = 0.f;
; #pragma unroll
;         for (int w = 0; w < 8; ++w) v += ldsf[w * 1024 + e];
;         const size_t row = (size_t)(rg * 16 + r);
;         pre[(MP + row) * 1024 + cg * 64 + c] = v + ALPHA * res[row * 1024 + cg * 64 + c];
;     }
;     __syncthreads();
	v_mfma_f32_16x16x32_bf16 v[4:7], v[24:27], v[28:31], v[4:7]
	global_load_dwordx4 v[28:31], v[52:53], off offset:320
	s_waitcnt vmcnt(5)
	v_mfma_f32_16x16x32_bf16 v[8:11], v[24:27], v[20:23], v[8:11]
	global_load_dwordx4 v[20:23], v[54:55], off offset:320
	global_load_dwordx4 v[44:47], v[56:57], off offset:320
	s_waitcnt vmcnt(6)
	v_mfma_f32_16x16x32_bf16 v[12:15], v[24:27], v[36:39], v[12:15]
	global_load_dwordx4 v[36:39], v[48:49], off offset:384
	s_waitcnt vmcnt(6)
	v_mfma_f32_16x16x32_bf16 v[0:3], v[24:27], v[40:43], v[0:3]
	global_load_dwordx4 v[24:27], v[50:51], off offset:384
	s_waitcnt vmcnt(5)
	v_mfma_f32_16x16x32_bf16 v[4:7], v[16:19], v[32:35], v[4:7]
	global_load_dwordx4 v[32:35], v[52:53], off offset:384
	s_waitcnt vmcnt(5)
	v_mfma_f32_16x16x32_bf16 v[8:11], v[16:19], v[28:31], v[8:11]
	global_load_dwordx4 v[28:31], v[54:55], off offset:384
	global_load_dwordx4 v[40:43], v[56:57], off offset:384
	s_load_dwordx2 s[0:1], s[0:1], 0x8
	s_waitcnt lgkmcnt(0)
	s_add_u32 s0, s0, s10
	s_waitcnt vmcnt(6)
	v_mfma_f32_16x16x32_bf16 v[12:15], v[16:19], v[20:23], v[12:15]
	global_load_dwordx4 v[20:23], v[48:49], off offset:448
	s_addc_u32 s1, s1, 0
	s_waitcnt vmcnt(6)
	v_mfma_f32_16x16x32_bf16 v[0:3], v[16:19], v[44:47], v[0:3]
	global_load_dwordx4 v[16:19], v[50:51], off offset:448
	s_waitcnt vmcnt(5)
	v_mfma_f32_16x16x32_bf16 v[4:7], v[36:39], v[24:27], v[4:7]
	global_load_dwordx4 v[24:27], v[52:53], off offset:448
	s_waitcnt vmcnt(5)
	v_mfma_f32_16x16x32_bf16 v[8:11], v[36:39], v[32:35], v[8:11]
	global_load_dwordx4 v[32:35], v[54:55], off offset:448
	s_waitcnt vmcnt(5)
	v_mfma_f32_16x16x32_bf16 v[12:15], v[36:39], v[28:31], v[12:15]
	global_load_dwordx4 v[28:31], v[56:57], off offset:448
	s_waitcnt vmcnt(5)
	v_mfma_f32_16x16x32_bf16 v[0:3], v[36:39], v[40:43], v[0:3]
	s_waitcnt vmcnt(3)
	v_mfma_f32_16x16x32_bf16 v[4:7], v[20:23], v[16:19], v[4:7]
	v_add3_u32 v16, s5, v135, v186
	s_waitcnt vmcnt(2)
	v_mfma_f32_16x16x32_bf16 v[8:11], v[20:23], v[24:27], v[8:11]
	s_waitcnt vmcnt(1)
	v_mfma_f32_16x16x32_bf16 v[12:15], v[20:23], v[32:35], v[12:15]
	s_waitcnt vmcnt(0)
	v_mfma_f32_16x16x32_bf16 v[0:3], v[20:23], v[28:31], v[0:3]
	s_nop 3
	ds_write2_b32 v16, v4, v8 offset1:16
	ds_write2_b32 v16, v5, v9 offset0:64 offset1:80
	ds_write2_b32 v16, v6, v10 offset0:128 offset1:144
	ds_write2_b32 v16, v7, v11 offset0:192 offset1:208
	ds_write2_b32 v16, v12, v0 offset0:32 offset1:48
	ds_write2_b32 v16, v13, v1 offset0:96 offset1:112
	ds_write2_b32 v16, v14, v2 offset0:160 offset1:176
	ds_write2_b32 v16, v15, v3 offset0:224 offset1:240
	v_add_u32_e32 v4, 0x200, v172
	v_or_b32_e32 v2, s4, v194
	v_lshrrev_b32_e32 v4, 6, v4
	v_ashrrev_i32_e32 v3, 31, v2
	v_add_u32_e32 v4, s4, v4
	v_lshl_add_u64 v[0:1], s[0:1], 0, v[128:129]
	v_lshlrev_b64 v[130:131], 12, v[2:3]
	v_ashrrev_i32_e32 v5, 31, v4
	v_lshl_add_u64 v[2:3], v[0:1], 0, v[130:131]
	v_lshlrev_b64 v[132:133], 12, v[4:5]
	s_waitcnt lgkmcnt(0)
	s_barrier
	v_lshl_add_u64 v[0:1], v[0:1], 0, v[132:133]
	v_mov_b32_e32 v20, v62
	v_mov_b32_e32 v21, v63
	ds_read2st64_b32 v[4:5], v173 offset1:8
	ds_read2st64_b32 v[6:7], v173 offset0:16 offset1:24
	ds_read2st64_b32 v[8:9], v173 offset0:32 offset1:40
	ds_read2st64_b32 v[10:11], v173 offset0:48 offset1:56
	ds_read2st64_b32 v[12:13], v173 offset0:64 offset1:72
	ds_read2st64_b32 v[14:15], v173 offset0:80 offset1:88
	ds_read2st64_b32 v[16:17], v173 offset0:96 offset1:104
	ds_read2st64_b32 v[18:19], v173 offset0:112 offset1:120
	s_waitcnt lgkmcnt(7)
	v_add_f32_e32 v4, 0, v4
	v_add_f32_e32 v5, 0, v5
	s_waitcnt lgkmcnt(6)
	v_add_f32_e32 v4, v4, v6
	v_add_f32_e32 v5, v5, v7
	s_waitcnt lgkmcnt(5)
	v_add_f32_e32 v4, v4, v8
	v_lshl_add_u64 v[0:1], s[12:13], 0, v[130:131]
	v_add_f32_e32 v5, v5, v9
	s_waitcnt lgkmcnt(4)
	v_add_f32_e32 v4, v4, v10
	v_lshl_add_u64 v[0:1], v[0:1], 0, s[10:11]
	v_add_f32_e32 v5, v5, v11
	s_waitcnt lgkmcnt(3)
	v_add_f32_e32 v4, v4, v12
	s_brev_b32 s0, 32
	v_lshl_add_u64 v[2:3], s[12:13], 0, v[132:133]
	v_lshl_add_u64 v[136:137], v[0:1], 0, v[128:129]
	v_add_f32_e32 v5, v5, v13
	s_waitcnt lgkmcnt(2)
	v_add_f32_e32 v4, v4, v14
	v_lshl_add_u64 v[2:3], v[2:3], 0, s[10:11]
	v_add_co_u32_e32 v0, vcc, s0, v136
	v_add_f32_e32 v5, v5, v15
	s_waitcnt lgkmcnt(1)
	v_add_f32_e32 v4, v4, v16
	v_lshl_add_u64 v[138:139], v[2:3], 0, v[128:129]
	v_addc_co_u32_e32 v1, vcc, 0, v137, vcc
	v_add_f32_e32 v5, v5, v17
	s_waitcnt lgkmcnt(0)
	v_add_f32_e32 v4, v4, v18
	v_add_co_u32_e32 v2, vcc, 0x4000000, v138
	v_add_f32_e32 v5, v5, v19
	s_nop 0
	v_addc_co_u32_e32 v3, vcc, 0, v139, vcc
	s_waitcnt vmcnt(1)
	v_fmac_f32_e32 v4, 0x3f9837f0, v20
	s_waitcnt vmcnt(0)
	v_fmac_f32_e32 v5, 0x3f9837f0, v21
	global_store_dword v[0:1], v4, off sc1
	global_store_dword v[2:3], v5, off sc1
	s_barrier

; #define MFMA16(a, b, c) __builtin_amdgcn_mfma_f32_16x16x32_bf16((a), (b), (c), 0, 0, 0)
; template <int K>
; __device__ __forceinline__ void skinny_sample_gemm(const bfu* __restrict__ A, const bfu* __restrict__ Bt, const float* __restrict__ res, float* __restrict__ pre, float* ldsf, int bid) {
;     const int tid = threadIdx.x, lane = tid & 63, wave = __builtin_amdgcn_readfirstlane(tid >> 6), l15 = lane & 15, quad = lane >> 4;
;     const int rg = bid >> 4, cg = bid & 15;
;     constexpr int KW = K / 8, NS = KW / 32;
;     const bfu* ap = A + (size_t)(MP + rg * 16 + l15) * K + wave * KW + quad * 8;
;     const bfu* bp = Bt + (size_t)(cg * 64 + l15) * K + wave * KW + quad * 8;
;     f32x4 acc[4];
; #pragma unroll
;     for (int nt = 0; nt < 4; ++nt) acc[nt] = (f32x4){0.f, 0.f, 0.f, 0.f};
; #pragma unroll
;     for (int ks = 0; ks < NS; ++ks) {
;         const bf16x8 af = ld8g(ap + ks * 32);
; #pragma unroll
;         for (int nt = 0; nt < 4; ++nt) acc[nt] = MFMA16(af, ld8g(bp + (size_t)nt * 16 * K + ks * 32), acc[nt]);
;     }
;     ...
;         const size_t row = (size_t)(rg * 16 + r);
;         pre[(MP + row) * 1024 + cg * 64 + c] = v + ALPHA * res[row * 1024 + cg * 64 + c];
.LBB0_1226:
	s_or_b64 exec, exec, s[0:1]
	s_add_u32 s24, s66, 0x1c00000
	v_readfirstlane_b32 s0, v172
	s_addc_u32 s25, s67, 0
	s_lshr_b32 s0, s0, 6
	s_waitcnt lgkmcnt(0)
	v_mul_u32_u24_e32 v0, 0xb00, v187
	s_mul_i32 s4, s0, 0x160
	s_mov_b32 s5, 0
	v_lshlrev_b32_e32 v44, 1, v0
	v_mov_b32_e32 v45, 0
	v_lshl_add_u64 v[4:5], s[24:25], 0, v[44:45]
	s_lshl_b64 s[4:5], s[4:5], 1
	s_movk_i32 s1, 0x1600
	v_mov_b64_e32 v[0:1], s[20:21]
	v_mad_i64_i32 v[0:1], s[6:7], v134, s1, v[0:1]
	v_lshlrev_b32_e32 v44, 1, v195
	v_lshl_add_u64 v[4:5], v[4:5], 0, s[4:5]
	v_lshl_add_u64 v[0:1], v[0:1], 0, s[4:5]
	v_lshl_add_u64 v[48:49], v[4:5], 0, v[44:45]
	s_mov_b32 s1, 0x16000
	v_lshl_add_u64 v[46:47], v[0:1], 0, v[44:45]
	v_add_co_u32_e32 v50, vcc, s1, v48
	s_barrier
	s_add_u32 s98, s66, s10
	s_addc_u32 s99, s67, 0
	s_add_u32 s98, s98, 0x30e00000
	s_addc_u32 s99, s99, 0
	v_mov_b32_e32 v60, v128
	v_mov_b32_e32 v61, 0
	v_lshl_add_u64 v[60:61], s[98:99], 0, v[60:61]
	v_lshl_add_u64 v[62:63], v[60:61], 0, v[130:131]
	v_lshl_add_u64 v[60:61], v[60:61], 0, v[132:133]
	global_load_dword v64, v[62:63], off
	global_load_dword v65, v[60:61], off
	global_load_dwordx4 v[0:3], v[46:47], off
	global_load_dwordx4 v[4:7], v[48:49], off
	s_mov_b32 s3, 0x2c000
	v_addc_co_u32_e32 v51, vcc, 0, v49, vcc
	v_add_co_u32_e32 v52, vcc, s3, v48
	s_mov_b32 s1, 0x42000
	s_nop 0
	v_addc_co_u32_e32 v53, vcc, 0, v49, vcc
	v_add_co_u32_e32 v54, vcc, s1, v48
	global_load_dwordx4 v[8:11], v[50:51], off
	global_load_dwordx4 v[12:15], v[46:47], off offset:64
	global_load_dwordx4 v[16:19], v[46:47], off offset:640
	global_load_dwordx4 v[20:23], v[52:53], off
	v_addc_co_u32_e32 v55, vcc, 0, v49, vcc
	global_load_dwordx4 v[24:27], v[50:51], off offset:64
	global_load_dwordx4 v[28:31], v[50:51], off offset:640
	global_load_dwordx4 v[32:35], v[54:55], off
	global_load_dwordx4 v[36:39], v[54:55], off offset:64
	s_lshl_b32 s0, s0, 12
	s_add_i32 s0, s0, 0
	v_mov_b32_e32 v129, v45
	s_waitcnt vmcnt(8)
	v_mfma_f32_16x16x32_bf16 v[4:7], v[0:3], v[4:7], 0
	s_waitcnt vmcnt(7)
	v_mfma_f32_16x16x32_bf16 v[8:11], v[0:3], v[8:11], 0
	s_waitcnt vmcnt(4)
	v_mfma_f32_16x16x32_bf16 v[20:23], v[0:3], v[20:23], 0
	s_waitcnt vmcnt(1)
	v_mfma_f32_16x16x32_bf16 v[0:3], v[0:3], v[32:35], 0
	global_load_dwordx4 v[32:35], v[48:49], off offset:64
	global_load_dwordx4 v[40:43], v[48:49], off offset:128
	v_mfma_f32_16x16x32_bf16 v[8:11], v[12:15], v[24:27], v[8:11]
	s_waitcnt vmcnt(2)
	v_mfma_f32_16x16x32_bf16 v[0:3], v[12:15], v[36:39], v[0:3]
	s_waitcnt vmcnt(1)
	v_mfma_f32_16x16x32_bf16 v[4:7], v[12:15], v[32:35], v[4:7]
	global_load_dwordx4 v[24:27], v[52:53], off offset:64
	global_load_dwordx4 v[32:35], v[52:53], off offset:128
	s_waitcnt vmcnt(1)
	v_mfma_f32_16x16x32_bf16 v[20:23], v[12:15], v[24:27], v[20:23]
	global_load_dwordx4 v[12:15], v[46:47], off offset:128
	global_load_dwordx4 v[24:27], v[46:47], off offset:192
	s_waitcnt vmcnt(1)
	v_mfma_f32_16x16x32_bf16 v[4:7], v[12:15], v[40:43], v[4:7]
	global_load_dwordx4 v[36:39], v[50:51], off offset:128
	global_load_dwordx4 v[40:43], v[50:51], off offset:192
	v_mfma_f32_16x16x32_bf16 v[20:23], v[12:15], v[32:35], v[20:23]
	s_waitcnt vmcnt(1)
	v_mfma_f32_16x16x32_bf16 v[8:11], v[12:15], v[36:39], v[8:11]
	global_load_dwordx4 v[32:35], v[54:55], off offset:128
	global_load_dwordx4 v[36:39], v[54:55], off offset:192
	s_waitcnt vmcnt(2)
	v_mfma_f32_16x16x32_bf16 v[8:11], v[24:27], v[40:43], v[8:11]
	s_waitcnt vmcnt(1)
	v_mfma_f32_16x16x32_bf16 v[0:3], v[12:15], v[32:35], v[0:3]
	global_load_dwordx4 v[12:15], v[48:49], off offset:192
	global_load_dwordx4 v[32:35], v[48:49], off offset:256
	s_waitcnt vmcnt(2)
	v_mfma_f32_16x16x32_bf16 v[0:3], v[24:27], v[36:39], v[0:3]
	s_waitcnt vmcnt(1)
	v_mfma_f32_16x16x32_bf16 v[4:7], v[24:27], v[12:15], v[4:7]
	global_load_dwordx4 v[12:15], v[52:53], off offset:192
	global_load_dwordx4 v[40:43], v[52:53], off offset:256
	s_waitcnt vmcnt(1)
	v_mfma_f32_16x16x32_bf16 v[12:15], v[24:27], v[12:15], v[20:23]
	s_nop 2
	global_load_dwordx4 v[20:23], v[46:47], off offset:256
	global_load_dwordx4 v[24:27], v[46:47], off offset:320
	s_waitcnt vmcnt(1)
	v_mfma_f32_16x16x32_bf16 v[4:7], v[20:23], v[32:35], v[4:7]
	global_load_dwordx4 v[32:35], v[50:51], off offset:256
	global_load_dwordx4 v[36:39], v[50:51], off offset:320
	v_mfma_f32_16x16x32_bf16 v[12:15], v[20:23], v[40:43], v[12:15]
	s_waitcnt vmcnt(1)
	v_mfma_f32_16x16x32_bf16 v[8:11], v[20:23], v[32:35], v[8:11]
	global_load_dwordx4 v[32:35], v[54:55], off offset:256
	global_load_dwordx4 v[40:43], v[54:55], off offset:320
	s_waitcnt vmcnt(2)
	v_mfma_f32_16x16x32_bf16 v[8:11], v[24:27], v[36:39], v[8:11]
	s_waitcnt vmcnt(1)
	v_mfma_f32_16x16x32_bf16 v[0:3], v[20:23], v[32:35], v[0:3]
	global_load_dwordx4 v[20:23], v[48:49], off offset:320
	global_load_dwordx4 v[32:35], v[48:49], off offset:384
	s_waitcnt vmcnt(2)
	v_mfma_f32_16x16x32_bf16 v[0:3], v[24:27], v[40:43], v[0:3]
	s_waitcnt vmcnt(1)
; #define MFMA16(a, b, c) __builtin_amdgcn_mfma_f32_16x16x32_bf16((a), (b), (c), 0, 0, 0)
; template <int K>
; __device__ __forceinline__ void skinny_sample_gemm(const bfu* __restrict__ A, const bfu* __restrict__ Bt, const float* __restrict__ res, float* __restrict__ pre, float* ldsf, int bid) {
;     ...
;     for (int ks = 0; ks < NS; ++ks) {
;         const bf16x8 af = ld8g(ap + ks * 32);
; #pragma unroll
;         for (int nt = 0; nt < 4; ++nt) acc[nt] = MFMA16(af, ld8g(bp + (size_t)nt * 16 * K + ks * 32), acc[nt]);
;     }
; #pragma unroll
;     for (int nt = 0; nt < 4; ++nt)
; #pragma unroll
;         for (int j = 0; j < 4; ++j) ldsf[wave * 1024 + (quad * 4 + j) * 64 + nt * 16 + l15] = acc[nt][j];
;     __syncthreads();
; #pragma unroll
;     for (int i = 0; i < 2; ++i) {
;         const int e = tid + 512 * i, r = e >> 6, c = e & 63;
;         float v = 0.f;
; #pragma unroll
;         for (int w = 0; w < 8; ++w) v += ldsf[w * 1024 + e];
;         const size_t row = (size_t)(rg * 16 + r);
;         pre[(MP + row) * 1024 + cg * 64 + c] = v + ALPHA * res[row * 1024 + cg * 64 + c];
;     }
;     __syncthreads();
	v_mfma_f32_16x16x32_bf16 v[4:7], v[24:27], v[20:23], v[4:7]
	global_load_dwordx4 v[20:23], v[52:53], off offset:320
	global_load_dwordx4 v[36:39], v[52:53], off offset:384
	s_waitcnt vmcnt(1)
	v_mfma_f32_16x16x32_bf16 v[12:15], v[24:27], v[20:23], v[12:15]
	global_load_dwordx4 v[20:23], v[46:47], off offset:384
	global_load_dwordx4 v[24:27], v[46:47], off offset:448
	s_waitcnt vmcnt(1)
	v_mfma_f32_16x16x32_bf16 v[4:7], v[20:23], v[32:35], v[4:7]
	global_load_dwordx4 v[32:35], v[50:51], off offset:384
	global_load_dwordx4 v[40:43], v[50:51], off offset:448
	v_mfma_f32_16x16x32_bf16 v[12:15], v[20:23], v[36:39], v[12:15]
	s_waitcnt vmcnt(1)
	v_mfma_f32_16x16x32_bf16 v[8:11], v[20:23], v[32:35], v[8:11]
	global_load_dwordx4 v[32:35], v[54:55], off offset:384
	global_load_dwordx4 v[36:39], v[54:55], off offset:448
	s_waitcnt vmcnt(2)
	v_mfma_f32_16x16x32_bf16 v[8:11], v[24:27], v[40:43], v[8:11]
	s_waitcnt vmcnt(1)
	v_mfma_f32_16x16x32_bf16 v[0:3], v[20:23], v[32:35], v[0:3]
	global_load_dwordx4 v[20:23], v[48:49], off offset:448
	global_load_dwordx4 v[32:35], v[48:49], off offset:512
	s_waitcnt vmcnt(2)
	v_mfma_f32_16x16x32_bf16 v[0:3], v[24:27], v[36:39], v[0:3]
	s_waitcnt vmcnt(1)
	v_mfma_f32_16x16x32_bf16 v[4:7], v[24:27], v[20:23], v[4:7]
	global_load_dwordx4 v[20:23], v[52:53], off offset:448
	global_load_dwordx4 v[40:43], v[52:53], off offset:512
	s_waitcnt vmcnt(1)
	v_mfma_f32_16x16x32_bf16 v[12:15], v[24:27], v[20:23], v[12:15]
	global_load_dwordx4 v[20:23], v[46:47], off offset:512
	global_load_dwordx4 v[24:27], v[46:47], off offset:576
	s_waitcnt vmcnt(1)
	v_mfma_f32_16x16x32_bf16 v[4:7], v[20:23], v[32:35], v[4:7]
	global_load_dwordx4 v[32:35], v[50:51], off offset:512
	global_load_dwordx4 v[36:39], v[50:51], off offset:576
	v_mfma_f32_16x16x32_bf16 v[12:15], v[20:23], v[40:43], v[12:15]
	s_waitcnt vmcnt(1)
	v_mfma_f32_16x16x32_bf16 v[8:11], v[20:23], v[32:35], v[8:11]
	global_load_dwordx4 v[32:35], v[54:55], off offset:512
	global_load_dwordx4 v[40:43], v[54:55], off offset:576
	s_waitcnt vmcnt(2)
	v_mfma_f32_16x16x32_bf16 v[8:11], v[24:27], v[36:39], v[8:11]
	v_mfma_f32_16x16x32_bf16 v[8:11], v[16:19], v[28:31], v[8:11]
	s_waitcnt vmcnt(1)
	v_mfma_f32_16x16x32_bf16 v[0:3], v[20:23], v[32:35], v[0:3]
	global_load_dwordx4 v[20:23], v[48:49], off offset:576
	global_load_dwordx4 v[32:35], v[48:49], off offset:640
	s_waitcnt vmcnt(2)
	v_mfma_f32_16x16x32_bf16 v[0:3], v[24:27], v[40:43], v[0:3]
	s_waitcnt vmcnt(1)
	v_mfma_f32_16x16x32_bf16 v[4:7], v[24:27], v[20:23], v[4:7]
	global_load_dwordx4 v[20:23], v[52:53], off offset:576
	global_load_dwordx4 v[36:39], v[52:53], off offset:640
	s_waitcnt vmcnt(2)
	v_mfma_f32_16x16x32_bf16 v[4:7], v[16:19], v[32:35], v[4:7]
	s_waitcnt vmcnt(1)
	v_mfma_f32_16x16x32_bf16 v[12:15], v[24:27], v[20:23], v[12:15]
	global_load_dwordx4 v[20:23], v[54:55], off offset:640
	v_add3_u32 v24, s0, v135, v186
	s_add_u32 s0, s66, s10
	s_waitcnt vmcnt(1)
	v_mfma_f32_16x16x32_bf16 v[12:15], v[16:19], v[36:39], v[12:15]
	s_addc_u32 s1, s67, 0
	ds_write2_b32 v24, v4, v8 offset1:16
	ds_write2_b32 v24, v5, v9 offset0:64 offset1:80
	ds_write2_b32 v24, v6, v10 offset0:128 offset1:144
	ds_write2_b32 v24, v7, v11 offset0:192 offset1:208
	s_add_u32 s3, s66, 0x38a0d000
	s_addc_u32 s33, s67, 0
	s_waitcnt vmcnt(0)
	v_mfma_f32_16x16x32_bf16 v[0:3], v[16:19], v[20:23], v[0:3]
	s_nop 7
	ds_write2_b32 v24, v12, v0 offset0:32 offset1:48
	ds_write2_b32 v24, v13, v1 offset0:96 offset1:112
	ds_write2_b32 v24, v14, v2 offset0:160 offset1:176
	ds_write2_b32 v24, v15, v3 offset0:224 offset1:240
	v_lshl_add_u64 v[0:1], s[0:1], 0, v[128:129]
	s_mov_b64 s[0:1], 0x30e00000
	v_lshl_add_u64 v[0:1], v[0:1], 0, s[0:1]
	v_lshl_add_u64 v[2:3], v[0:1], 0, v[130:131]
	s_waitcnt lgkmcnt(0)
	s_barrier
	v_lshl_add_u64 v[0:1], v[0:1], 0, v[132:133]
	v_mov_b32_e32 v16, v64
	v_mov_b32_e32 v17, v65
	ds_read2st64_b32 v[0:1], v173 offset1:8
	ds_read2st64_b32 v[2:3], v173 offset0:16 offset1:24
	ds_read2st64_b32 v[4:5], v173 offset0:32 offset1:40
	ds_read2st64_b32 v[6:7], v173 offset0:48 offset1:56
	ds_read2st64_b32 v[8:9], v173 offset0:64 offset1:72
	ds_read2st64_b32 v[10:11], v173 offset0:80 offset1:88
	ds_read2st64_b32 v[12:13], v173 offset0:96 offset1:104
	ds_read2st64_b32 v[14:15], v173 offset0:112 offset1:120
	s_waitcnt lgkmcnt(7)
	v_add_f32_e32 v0, 0, v0
	v_add_f32_e32 v1, 0, v1
	s_waitcnt lgkmcnt(6)
	v_add_f32_e32 v0, v0, v2
	v_add_f32_e32 v1, v1, v3
	s_waitcnt lgkmcnt(5)
	v_add_f32_e32 v0, v0, v4
	v_add_f32_e32 v1, v1, v5
	s_waitcnt lgkmcnt(4)
	v_add_f32_e32 v0, v0, v6
	v_add_f32_e32 v1, v1, v7
	s_waitcnt lgkmcnt(3)
	v_add_f32_e32 v0, v0, v8
	v_add_f32_e32 v1, v1, v9
	s_waitcnt lgkmcnt(2)
	v_add_f32_e32 v0, v0, v10
	v_add_f32_e32 v1, v1, v11
	s_waitcnt lgkmcnt(1)
	v_add_f32_e32 v0, v0, v12
	v_add_f32_e32 v1, v1, v13
	s_waitcnt lgkmcnt(0)
	v_add_f32_e32 v0, v0, v14
	v_add_f32_e32 v1, v1, v15
	s_waitcnt vmcnt(1)
	v_fmac_f32_e32 v0, 0x3f9837f0, v16
	s_waitcnt vmcnt(0)
	v_fmac_f32_e32 v1, 0x3f9837f0, v17
	global_store_dword v[136:137], v0, off sc1
	global_store_dword v[138:139], v1, off sc1
	s_barrier
